# sample-group GEMM (4-item variant): both K-chunks' 32 fragment loads issued up front, 64 MFMAs behind one counted ladder (single trip)
# baseline (speedup 1.0000x reference)
.LBB0_660:
	s_lshl_b64 s[10:11], s[10:11], 1
	v_lshl_add_u64 v[92:93], v[70:71], 0, s[10:11]
	v_add_co_u32_e32 v116, vcc, s16, v92
	v_lshl_add_u64 v[96:97], v[72:73], 0, s[10:11]
	s_nop 0
	v_addc_co_u32_e32 v117, vcc, 0, v93, vcc
	v_add_co_u32_e32 v124, vcc, s17, v92
	global_load_dwordx4 v[164:167], v[96:97], off offset:128
	global_load_dwordx4 v[88:91], v[96:97], off
	s_nop 0
	v_addc_co_u32_e32 v125, vcc, 0, v93, vcc
	v_add_co_u32_e32 v134, vcc, s18, v92
	global_load_dwordx4 v[168:171], v[92:93], off offset:128
	global_load_dwordx4 v[84:87], v[92:93], off
	s_nop 0
	v_addc_co_u32_e32 v135, vcc, 0, v93, vcc
	v_add_co_u32_e32 v138, vcc, s16, v96
	s_mov_b64 s[10:11], 64
	s_nop 0
	v_addc_co_u32_e32 v139, vcc, 0, v97, vcc
	v_add_co_u32_e32 v140, vcc, s17, v96
	s_nop 1
	v_addc_co_u32_e32 v141, vcc, 0, v97, vcc
	v_add_co_u32_e32 v142, vcc, s18, v96
	s_nop 1
	v_addc_co_u32_e32 v143, vcc, 0, v97, vcc
	global_load_dwordx4 v[172:175], v[92:93], off offset:192
	global_load_dwordx4 v[92:95], v[92:93], off offset:64
	s_nop 0
	global_load_dwordx4 v[176:179], v[96:97], off offset:192
	global_load_dwordx4 v[96:99], v[96:97], off offset:64
	s_nop 0
	global_load_dwordx4 v[180:183], v[116:117], off offset:128
	global_load_dwordx4 v[100:103], v[116:117], off
	global_load_dwordx4 v[184:187], v[124:125], off offset:128
	global_load_dwordx4 v[104:107], v[124:125], off
	global_load_dwordx4 v[188:191], v[134:135], off offset:128
	global_load_dwordx4 v[108:111], v[134:135], off
	global_load_dwordx4 v[192:195], v[138:139], off offset:128
	global_load_dwordx4 v[112:115], v[138:139], off
	s_nop 0
	global_load_dwordx4 v[196:199], v[116:117], off offset:192
	global_load_dwordx4 v[116:119], v[116:117], off offset:64
	global_load_dwordx4 v[200:203], v[140:141], off offset:128
	global_load_dwordx4 v[120:123], v[140:141], off
	s_nop 0
	global_load_dwordx4 v[204:207], v[124:125], off offset:192
	global_load_dwordx4 v[124:127], v[124:125], off offset:64
	s_nop 0
	global_load_dwordx4 v[208:211], v[142:143], off offset:128
	global_load_dwordx4 v[130:133], v[142:143], off
	s_nop 0
	global_load_dwordx4 v[212:215], v[134:135], off offset:192
	global_load_dwordx4 v[134:137], v[134:135], off offset:64
	s_andn2_b64 vcc, exec, s[8:9]
	global_load_dwordx4 v[216:219], v[142:143], off offset:192
	global_load_dwordx4 v[142:145], v[142:143], off offset:64
	s_mov_b64 s[8:9], 0
	global_load_dwordx4 v[220:223], v[138:139], off offset:192
	global_load_dwordx4 v[160:163], v[138:139], off offset:64
	s_nop 0
	global_load_dwordx4 v[224:227], v[140:141], off offset:192
	global_load_dwordx4 v[138:141], v[140:141], off offset:64
	s_waitcnt vmcnt(28)
	v_mfma_f32_16x16x32_bf16 v[8:11], v[88:91], v[84:87], v[8:11]
	s_waitcnt vmcnt(22)
	v_mfma_f32_16x16x32_bf16 v[24:27], v[88:91], v[100:103], v[24:27]
	s_waitcnt vmcnt(20)
	v_mfma_f32_16x16x32_bf16 v[36:39], v[88:91], v[104:107], v[36:39]
	s_waitcnt vmcnt(18)
	v_mfma_f32_16x16x32_bf16 v[48:51], v[88:91], v[108:111], v[48:51]
	s_waitcnt vmcnt(16)
	v_mfma_f32_16x16x32_bf16 v[0:3], v[112:115], v[84:87], v[0:3]
	s_waitcnt vmcnt(12)
	v_mfma_f32_16x16x32_bf16 v[4:7], v[120:123], v[84:87], v[4:7]
	s_waitcnt vmcnt(8)
	v_mfma_f32_16x16x32_bf16 v[12:15], v[130:133], v[84:87], v[12:15]
	v_mfma_f32_16x16x32_bf16 v[16:19], v[112:115], v[100:103], v[16:19]
	v_mfma_f32_16x16x32_bf16 v[20:23], v[120:123], v[100:103], v[20:23]
	v_mfma_f32_16x16x32_bf16 v[28:31], v[130:133], v[100:103], v[28:31]
	v_mfma_f32_16x16x32_bf16 v[32:35], v[112:115], v[104:107], v[32:35]
	v_mfma_f32_16x16x32_bf16 v[40:43], v[120:123], v[104:107], v[40:43]
	v_mfma_f32_16x16x32_bf16 v[44:47], v[130:133], v[104:107], v[44:47]
	v_mfma_f32_16x16x32_bf16 v[52:55], v[112:115], v[108:111], v[52:55]
	v_mfma_f32_16x16x32_bf16 v[56:59], v[120:123], v[108:111], v[56:59]
	v_mfma_f32_16x16x32_bf16 v[60:63], v[130:133], v[108:111], v[60:63]
	v_mfma_f32_16x16x32_bf16 v[8:11], v[96:99], v[92:95], v[8:11]
	v_mfma_f32_16x16x32_bf16 v[24:27], v[96:99], v[116:119], v[24:27]
	v_mfma_f32_16x16x32_bf16 v[36:39], v[96:99], v[124:127], v[36:39]
	s_waitcnt vmcnt(6)
	v_mfma_f32_16x16x32_bf16 v[48:51], v[96:99], v[134:137], v[48:51]
	s_waitcnt vmcnt(2)
	v_mfma_f32_16x16x32_bf16 v[0:3], v[160:163], v[92:95], v[0:3]
	s_waitcnt vmcnt(0)
	v_mfma_f32_16x16x32_bf16 v[4:7], v[138:141], v[92:95], v[4:7]
	v_mfma_f32_16x16x32_bf16 v[12:15], v[142:145], v[92:95], v[12:15]
	v_mfma_f32_16x16x32_bf16 v[16:19], v[160:163], v[116:119], v[16:19]
	v_mfma_f32_16x16x32_bf16 v[20:23], v[138:141], v[116:119], v[20:23]
	v_mfma_f32_16x16x32_bf16 v[28:31], v[142:145], v[116:119], v[28:31]
	v_mfma_f32_16x16x32_bf16 v[32:35], v[160:163], v[124:127], v[32:35]
	v_mfma_f32_16x16x32_bf16 v[40:43], v[138:141], v[124:127], v[40:43]
	v_mfma_f32_16x16x32_bf16 v[44:47], v[142:145], v[124:127], v[44:47]
	v_mfma_f32_16x16x32_bf16 v[52:55], v[160:163], v[134:137], v[52:55]
	v_mfma_f32_16x16x32_bf16 v[56:59], v[138:141], v[134:137], v[56:59]
	v_mfma_f32_16x16x32_bf16 v[60:63], v[142:145], v[134:137], v[60:63]
	v_mfma_f32_16x16x32_bf16 v[8:11], v[164:167], v[168:171], v[8:11]
	v_mfma_f32_16x16x32_bf16 v[24:27], v[164:167], v[180:183], v[24:27]
	v_mfma_f32_16x16x32_bf16 v[36:39], v[164:167], v[184:187], v[36:39]
	v_mfma_f32_16x16x32_bf16 v[48:51], v[164:167], v[188:191], v[48:51]
	v_mfma_f32_16x16x32_bf16 v[0:3], v[192:195], v[168:171], v[0:3]
	v_mfma_f32_16x16x32_bf16 v[4:7], v[200:203], v[168:171], v[4:7]
	v_mfma_f32_16x16x32_bf16 v[12:15], v[208:211], v[168:171], v[12:15]
	v_mfma_f32_16x16x32_bf16 v[16:19], v[192:195], v[180:183], v[16:19]
	v_mfma_f32_16x16x32_bf16 v[20:23], v[200:203], v[180:183], v[20:23]
	v_mfma_f32_16x16x32_bf16 v[28:31], v[208:211], v[180:183], v[28:31]
	v_mfma_f32_16x16x32_bf16 v[32:35], v[192:195], v[184:187], v[32:35]
	v_mfma_f32_16x16x32_bf16 v[40:43], v[200:203], v[184:187], v[40:43]
	v_mfma_f32_16x16x32_bf16 v[44:47], v[208:211], v[184:187], v[44:47]
	v_mfma_f32_16x16x32_bf16 v[52:55], v[192:195], v[188:191], v[52:55]
	v_mfma_f32_16x16x32_bf16 v[56:59], v[200:203], v[188:191], v[56:59]
	v_mfma_f32_16x16x32_bf16 v[60:63], v[208:211], v[188:191], v[60:63]
	v_mfma_f32_16x16x32_bf16 v[8:11], v[176:179], v[172:175], v[8:11]
	v_mfma_f32_16x16x32_bf16 v[24:27], v[176:179], v[196:199], v[24:27]
	v_mfma_f32_16x16x32_bf16 v[36:39], v[176:179], v[204:207], v[36:39]
	v_mfma_f32_16x16x32_bf16 v[48:51], v[176:179], v[212:215], v[48:51]
	v_mfma_f32_16x16x32_bf16 v[0:3], v[220:223], v[172:175], v[0:3]
	v_mfma_f32_16x16x32_bf16 v[4:7], v[224:227], v[172:175], v[4:7]
	v_mfma_f32_16x16x32_bf16 v[12:15], v[216:219], v[172:175], v[12:15]
	v_mfma_f32_16x16x32_bf16 v[16:19], v[220:223], v[196:199], v[16:19]
	v_mfma_f32_16x16x32_bf16 v[20:23], v[224:227], v[196:199], v[20:23]
	v_mfma_f32_16x16x32_bf16 v[28:31], v[216:219], v[196:199], v[28:31]
	v_mfma_f32_16x16x32_bf16 v[32:35], v[220:223], v[204:207], v[32:35]
	v_mfma_f32_16x16x32_bf16 v[40:43], v[224:227], v[204:207], v[40:43]
	v_mfma_f32_16x16x32_bf16 v[44:47], v[216:219], v[204:207], v[44:47]
	v_mfma_f32_16x16x32_bf16 v[52:55], v[220:223], v[212:215], v[52:55]
	v_mfma_f32_16x16x32_bf16 v[56:59], v[224:227], v[212:215], v[56:59]
	v_mfma_f32_16x16x32_bf16 v[60:63], v[216:219], v[212:215], v[60:63]
	s_lshl_b32 s8, s12, 12
	s_and_b32 s8, s8, 0x1c0000
	s_and_b32 s9, s14, 0xfc0
	s_or_b32 s8, s9, s8
	v_add_lshl_u32 v64, s8, v76, 1
	v_lshl_add_u64 v[70:71], s[46:47], 0, v[64:65]
	s_barrier
	ds_write_b128 v80, v[8:11]
	ds_write_b128 v81, v[0:3]
	ds_write_b128 v82, v[4:7]
	ds_write_b128 v83, v[12:15]
	ds_write_b128 v80, v[24:27] offset:4096
	ds_write_b128 v81, v[16:19] offset:4096
	ds_write_b128 v82, v[20:23] offset:4096
	ds_write_b128 v83, v[28:31] offset:4096
	ds_write_b128 v80, v[36:39] offset:8192
	ds_write_b128 v81, v[32:35] offset:8192
	ds_write_b128 v82, v[40:43] offset:8192
	ds_write_b128 v83, v[44:47] offset:8192
	ds_write_b128 v80, v[48:51] offset:12288
	ds_write_b128 v81, v[52:55] offset:12288
	ds_write_b128 v82, v[56:59] offset:12288
	ds_write_b128 v83, v[60:63] offset:12288
	s_mov_b64 s[8:9], 0
	v_mov_b32_e32 v0, v78
	v_mov_b32_e32 v1, v77
	v_mov_b32_e32 v2, v75
	s_waitcnt lgkmcnt(0)
	s_barrier

.LBB0_710:
	s_lshl_b64 s[10:11], s[10:11], 1
	v_lshl_add_u64 v[92:93], v[70:71], 0, s[10:11]
	v_add_co_u32_e32 v116, vcc, s16, v92
	v_lshl_add_u64 v[96:97], v[72:73], 0, s[10:11]
	s_nop 0
	v_addc_co_u32_e32 v117, vcc, 0, v93, vcc
	v_add_co_u32_e32 v124, vcc, s17, v92
	global_load_dwordx4 v[164:167], v[96:97], off offset:128
	global_load_dwordx4 v[88:91], v[96:97], off
	s_nop 0
	v_addc_co_u32_e32 v125, vcc, 0, v93, vcc
	v_add_co_u32_e32 v134, vcc, s18, v92
	global_load_dwordx4 v[168:171], v[92:93], off offset:128
	global_load_dwordx4 v[84:87], v[92:93], off
	s_nop 0
	v_addc_co_u32_e32 v135, vcc, 0, v93, vcc
	v_add_co_u32_e32 v138, vcc, s16, v96
	s_mov_b64 s[10:11], 64
	s_nop 0
	v_addc_co_u32_e32 v139, vcc, 0, v97, vcc
	v_add_co_u32_e32 v140, vcc, s17, v96
	s_nop 1
	v_addc_co_u32_e32 v141, vcc, 0, v97, vcc
	v_add_co_u32_e32 v142, vcc, s18, v96
	s_nop 1
	v_addc_co_u32_e32 v143, vcc, 0, v97, vcc
	global_load_dwordx4 v[172:175], v[92:93], off offset:192
	global_load_dwordx4 v[92:95], v[92:93], off offset:64
	s_nop 0
	global_load_dwordx4 v[176:179], v[96:97], off offset:192
	global_load_dwordx4 v[96:99], v[96:97], off offset:64
	s_nop 0
	global_load_dwordx4 v[180:183], v[116:117], off offset:128
	global_load_dwordx4 v[100:103], v[116:117], off
	global_load_dwordx4 v[184:187], v[124:125], off offset:128
	global_load_dwordx4 v[104:107], v[124:125], off
	global_load_dwordx4 v[188:191], v[134:135], off offset:128
	global_load_dwordx4 v[108:111], v[134:135], off
	global_load_dwordx4 v[192:195], v[138:139], off offset:128
	global_load_dwordx4 v[112:115], v[138:139], off
	s_nop 0
	global_load_dwordx4 v[196:199], v[116:117], off offset:192
	global_load_dwordx4 v[116:119], v[116:117], off offset:64
	global_load_dwordx4 v[200:203], v[140:141], off offset:128
	global_load_dwordx4 v[120:123], v[140:141], off
	s_nop 0
	global_load_dwordx4 v[204:207], v[124:125], off offset:192
	global_load_dwordx4 v[124:127], v[124:125], off offset:64
	s_nop 0
	global_load_dwordx4 v[208:211], v[142:143], off offset:128
	global_load_dwordx4 v[130:133], v[142:143], off
	s_nop 0
	global_load_dwordx4 v[212:215], v[134:135], off offset:192
	global_load_dwordx4 v[134:137], v[134:135], off offset:64
	s_andn2_b64 vcc, exec, s[8:9]
	global_load_dwordx4 v[216:219], v[142:143], off offset:192
	global_load_dwordx4 v[142:145], v[142:143], off offset:64
	s_mov_b64 s[8:9], 0
	global_load_dwordx4 v[220:223], v[138:139], off offset:192
	global_load_dwordx4 v[160:163], v[138:139], off offset:64
	s_nop 0
	global_load_dwordx4 v[224:227], v[140:141], off offset:192
	global_load_dwordx4 v[138:141], v[140:141], off offset:64
	s_waitcnt vmcnt(28)
	v_mfma_f32_16x16x32_bf16 v[8:11], v[88:91], v[84:87], v[8:11]
	s_waitcnt vmcnt(22)
	v_mfma_f32_16x16x32_bf16 v[24:27], v[88:91], v[100:103], v[24:27]
	s_waitcnt vmcnt(20)
	v_mfma_f32_16x16x32_bf16 v[36:39], v[88:91], v[104:107], v[36:39]
	s_waitcnt vmcnt(18)
	v_mfma_f32_16x16x32_bf16 v[48:51], v[88:91], v[108:111], v[48:51]
	s_waitcnt vmcnt(16)
	v_mfma_f32_16x16x32_bf16 v[0:3], v[112:115], v[84:87], v[0:3]
	s_waitcnt vmcnt(12)
	v_mfma_f32_16x16x32_bf16 v[4:7], v[120:123], v[84:87], v[4:7]
	s_waitcnt vmcnt(8)
	v_mfma_f32_16x16x32_bf16 v[12:15], v[130:133], v[84:87], v[12:15]
	v_mfma_f32_16x16x32_bf16 v[16:19], v[112:115], v[100:103], v[16:19]
	v_mfma_f32_16x16x32_bf16 v[20:23], v[120:123], v[100:103], v[20:23]
	v_mfma_f32_16x16x32_bf16 v[28:31], v[130:133], v[100:103], v[28:31]
	v_mfma_f32_16x16x32_bf16 v[32:35], v[112:115], v[104:107], v[32:35]
	v_mfma_f32_16x16x32_bf16 v[40:43], v[120:123], v[104:107], v[40:43]
	v_mfma_f32_16x16x32_bf16 v[44:47], v[130:133], v[104:107], v[44:47]
	v_mfma_f32_16x16x32_bf16 v[52:55], v[112:115], v[108:111], v[52:55]
	v_mfma_f32_16x16x32_bf16 v[56:59], v[120:123], v[108:111], v[56:59]
	v_mfma_f32_16x16x32_bf16 v[60:63], v[130:133], v[108:111], v[60:63]
	v_mfma_f32_16x16x32_bf16 v[8:11], v[96:99], v[92:95], v[8:11]
	v_mfma_f32_16x16x32_bf16 v[24:27], v[96:99], v[116:119], v[24:27]
	v_mfma_f32_16x16x32_bf16 v[36:39], v[96:99], v[124:127], v[36:39]
	s_waitcnt vmcnt(6)
	v_mfma_f32_16x16x32_bf16 v[48:51], v[96:99], v[134:137], v[48:51]
	s_waitcnt vmcnt(2)
	v_mfma_f32_16x16x32_bf16 v[0:3], v[160:163], v[92:95], v[0:3]
	s_waitcnt vmcnt(0)
	v_mfma_f32_16x16x32_bf16 v[4:7], v[138:141], v[92:95], v[4:7]
	v_mfma_f32_16x16x32_bf16 v[12:15], v[142:145], v[92:95], v[12:15]
	v_mfma_f32_16x16x32_bf16 v[16:19], v[160:163], v[116:119], v[16:19]
	v_mfma_f32_16x16x32_bf16 v[20:23], v[138:141], v[116:119], v[20:23]
	v_mfma_f32_16x16x32_bf16 v[28:31], v[142:145], v[116:119], v[28:31]
	v_mfma_f32_16x16x32_bf16 v[32:35], v[160:163], v[124:127], v[32:35]
	v_mfma_f32_16x16x32_bf16 v[40:43], v[138:141], v[124:127], v[40:43]
	v_mfma_f32_16x16x32_bf16 v[44:47], v[142:145], v[124:127], v[44:47]
	v_mfma_f32_16x16x32_bf16 v[52:55], v[160:163], v[134:137], v[52:55]
	v_mfma_f32_16x16x32_bf16 v[56:59], v[138:141], v[134:137], v[56:59]
	v_mfma_f32_16x16x32_bf16 v[60:63], v[142:145], v[134:137], v[60:63]
	v_mfma_f32_16x16x32_bf16 v[8:11], v[164:167], v[168:171], v[8:11]
	v_mfma_f32_16x16x32_bf16 v[24:27], v[164:167], v[180:183], v[24:27]
	v_mfma_f32_16x16x32_bf16 v[36:39], v[164:167], v[184:187], v[36:39]
	v_mfma_f32_16x16x32_bf16 v[48:51], v[164:167], v[188:191], v[48:51]
	v_mfma_f32_16x16x32_bf16 v[0:3], v[192:195], v[168:171], v[0:3]
	v_mfma_f32_16x16x32_bf16 v[4:7], v[200:203], v[168:171], v[4:7]
	v_mfma_f32_16x16x32_bf16 v[12:15], v[208:211], v[168:171], v[12:15]
	v_mfma_f32_16x16x32_bf16 v[16:19], v[192:195], v[180:183], v[16:19]
	v_mfma_f32_16x16x32_bf16 v[20:23], v[200:203], v[180:183], v[20:23]
	v_mfma_f32_16x16x32_bf16 v[28:31], v[208:211], v[180:183], v[28:31]
	v_mfma_f32_16x16x32_bf16 v[32:35], v[192:195], v[184:187], v[32:35]
	v_mfma_f32_16x16x32_bf16 v[40:43], v[200:203], v[184:187], v[40:43]
	v_mfma_f32_16x16x32_bf16 v[44:47], v[208:211], v[184:187], v[44:47]
	v_mfma_f32_16x16x32_bf16 v[52:55], v[192:195], v[188:191], v[52:55]
	v_mfma_f32_16x16x32_bf16 v[56:59], v[200:203], v[188:191], v[56:59]
	v_mfma_f32_16x16x32_bf16 v[60:63], v[208:211], v[188:191], v[60:63]
	v_mfma_f32_16x16x32_bf16 v[8:11], v[176:179], v[172:175], v[8:11]
	v_mfma_f32_16x16x32_bf16 v[24:27], v[176:179], v[196:199], v[24:27]
	v_mfma_f32_16x16x32_bf16 v[36:39], v[176:179], v[204:207], v[36:39]
	v_mfma_f32_16x16x32_bf16 v[48:51], v[176:179], v[212:215], v[48:51]
	v_mfma_f32_16x16x32_bf16 v[0:3], v[220:223], v[172:175], v[0:3]
	v_mfma_f32_16x16x32_bf16 v[4:7], v[224:227], v[172:175], v[4:7]
	v_mfma_f32_16x16x32_bf16 v[12:15], v[216:219], v[172:175], v[12:15]
	v_mfma_f32_16x16x32_bf16 v[16:19], v[220:223], v[196:199], v[16:19]
	v_mfma_f32_16x16x32_bf16 v[20:23], v[224:227], v[196:199], v[20:23]
	v_mfma_f32_16x16x32_bf16 v[28:31], v[216:219], v[196:199], v[28:31]
	v_mfma_f32_16x16x32_bf16 v[32:35], v[220:223], v[204:207], v[32:35]
	v_mfma_f32_16x16x32_bf16 v[40:43], v[224:227], v[204:207], v[40:43]
	v_mfma_f32_16x16x32_bf16 v[44:47], v[216:219], v[204:207], v[44:47]
	v_mfma_f32_16x16x32_bf16 v[52:55], v[220:223], v[212:215], v[52:55]
	v_mfma_f32_16x16x32_bf16 v[56:59], v[224:227], v[212:215], v[56:59]
	v_mfma_f32_16x16x32_bf16 v[60:63], v[216:219], v[212:215], v[60:63]
	s_lshl_b32 s8, s12, 12
	s_and_b32 s8, s8, 0x1c0000
	s_and_b32 s9, s14, 0xfc0
	s_or_b32 s8, s9, s8
	v_add_lshl_u32 v64, s8, v76, 1
	v_lshl_add_u64 v[70:71], s[46:47], 0, v[64:65]
	s_waitcnt lgkmcnt(0)
	s_barrier
	ds_write_b128 v80, v[8:11]
	ds_write_b128 v81, v[0:3]
	ds_write_b128 v82, v[4:7]
	ds_write_b128 v83, v[12:15]
	ds_write_b128 v80, v[24:27] offset:4096
	ds_write_b128 v81, v[16:19] offset:4096
	ds_write_b128 v82, v[20:23] offset:4096
	ds_write_b128 v83, v[28:31] offset:4096
	ds_write_b128 v80, v[36:39] offset:8192
	ds_write_b128 v81, v[32:35] offset:8192
	ds_write_b128 v82, v[40:43] offset:8192
	ds_write_b128 v83, v[44:47] offset:8192
	ds_write_b128 v80, v[48:51] offset:12288
	ds_write_b128 v81, v[52:55] offset:12288
	ds_write_b128 v82, v[56:59] offset:12288
	ds_write_b128 v83, v[60:63] offset:12288
	s_mov_b64 s[8:9], 0
	v_mov_b32_e32 v0, v78
	v_mov_b32_e32 v1, v77
	v_mov_b32_e32 v2, v75
	s_waitcnt lgkmcnt(0)
	s_barrier

.LBB0_1097:
	s_lshl_b64 s[8:9], s[8:9], 1
	v_lshl_add_u64 v[104:105], v[72:73], 0, s[8:9]
	v_add_co_u32_e32 v130, vcc, s12, v104
	v_lshl_add_u64 v[108:109], v[74:75], 0, s[8:9]
	s_nop 0
	v_addc_co_u32_e32 v131, vcc, 0, v105, vcc
	v_add_co_u32_e32 v138, vcc, s10, v104
	global_load_dwordx4 v[164:167], v[108:109], off offset:128
	global_load_dwordx4 v[100:103], v[108:109], off
	s_nop 0
	v_addc_co_u32_e32 v139, vcc, 0, v105, vcc
	v_add_co_u32_e32 v148, vcc, s11, v104
	global_load_dwordx4 v[168:171], v[104:105], off offset:128
	global_load_dwordx4 v[96:99], v[104:105], off
	s_nop 0
	v_addc_co_u32_e32 v149, vcc, 0, v105, vcc
	v_add_co_u32_e32 v152, vcc, s12, v108
	s_mov_b64 s[8:9], 64
	s_nop 0
	v_addc_co_u32_e32 v153, vcc, 0, v109, vcc
	v_add_co_u32_e32 v154, vcc, s10, v108
	s_nop 1
	v_addc_co_u32_e32 v155, vcc, 0, v109, vcc
	v_add_co_u32_e32 v156, vcc, s11, v108
	s_nop 1
	v_addc_co_u32_e32 v157, vcc, 0, v109, vcc
	global_load_dwordx4 v[172:175], v[104:105], off offset:192
	global_load_dwordx4 v[104:107], v[104:105], off offset:64
	s_nop 0
	global_load_dwordx4 v[176:179], v[108:109], off offset:192
	global_load_dwordx4 v[108:111], v[108:109], off offset:64
	s_nop 0
	global_load_dwordx4 v[180:183], v[130:131], off offset:128
	global_load_dwordx4 v[112:115], v[130:131], off
	global_load_dwordx4 v[184:187], v[138:139], off offset:128
	global_load_dwordx4 v[116:119], v[138:139], off
	global_load_dwordx4 v[188:191], v[148:149], off offset:128
	global_load_dwordx4 v[120:123], v[148:149], off
	global_load_dwordx4 v[192:195], v[152:153], off offset:128
	global_load_dwordx4 v[124:127], v[152:153], off
	s_nop 0
	global_load_dwordx4 v[196:199], v[130:131], off offset:192
	global_load_dwordx4 v[130:133], v[130:131], off offset:64
	global_load_dwordx4 v[200:203], v[154:155], off offset:128
	global_load_dwordx4 v[134:137], v[154:155], off
	s_nop 0
	global_load_dwordx4 v[204:207], v[138:139], off offset:192
	global_load_dwordx4 v[138:141], v[138:139], off offset:64
	s_nop 0
	global_load_dwordx4 v[208:211], v[156:157], off offset:128
	global_load_dwordx4 v[142:145], v[156:157], off
	s_nop 0
	global_load_dwordx4 v[212:215], v[148:149], off offset:192
	global_load_dwordx4 v[148:151], v[148:149], off offset:64
	s_andn2_b64 vcc, exec, s[6:7]
	global_load_dwordx4 v[216:219], v[156:157], off offset:192
	global_load_dwordx4 v[156:159], v[156:157], off offset:64
	s_mov_b64 s[6:7], 0
	global_load_dwordx4 v[220:223], v[152:153], off offset:192
	global_load_dwordx4 v[160:163], v[152:153], off offset:64
	s_nop 0
	global_load_dwordx4 v[224:227], v[154:155], off offset:192
	global_load_dwordx4 v[152:155], v[154:155], off offset:64
	s_waitcnt vmcnt(28)
	v_mfma_f32_16x16x32_bf16 v[8:11], v[100:103], v[96:99], v[8:11]
	s_waitcnt vmcnt(22)
	v_mfma_f32_16x16x32_bf16 v[24:27], v[100:103], v[112:115], v[24:27]
	s_waitcnt vmcnt(20)
	v_mfma_f32_16x16x32_bf16 v[36:39], v[100:103], v[116:119], v[36:39]
	s_waitcnt vmcnt(18)
	v_mfma_f32_16x16x32_bf16 v[48:51], v[100:103], v[120:123], v[48:51]
	s_waitcnt vmcnt(16)
	v_mfma_f32_16x16x32_bf16 v[0:3], v[124:127], v[96:99], v[0:3]
	s_waitcnt vmcnt(12)
	v_mfma_f32_16x16x32_bf16 v[4:7], v[134:137], v[96:99], v[4:7]
	s_waitcnt vmcnt(8)
	v_mfma_f32_16x16x32_bf16 v[12:15], v[142:145], v[96:99], v[12:15]
	v_mfma_f32_16x16x32_bf16 v[16:19], v[124:127], v[112:115], v[16:19]
	v_mfma_f32_16x16x32_bf16 v[20:23], v[134:137], v[112:115], v[20:23]
	v_mfma_f32_16x16x32_bf16 v[28:31], v[142:145], v[112:115], v[28:31]
	v_mfma_f32_16x16x32_bf16 v[32:35], v[124:127], v[116:119], v[32:35]
	v_mfma_f32_16x16x32_bf16 v[40:43], v[134:137], v[116:119], v[40:43]
	v_mfma_f32_16x16x32_bf16 v[44:47], v[142:145], v[116:119], v[44:47]
	v_mfma_f32_16x16x32_bf16 v[52:55], v[124:127], v[120:123], v[52:55]
	v_mfma_f32_16x16x32_bf16 v[56:59], v[134:137], v[120:123], v[56:59]
	v_mfma_f32_16x16x32_bf16 v[60:63], v[142:145], v[120:123], v[60:63]
	v_mfma_f32_16x16x32_bf16 v[8:11], v[108:111], v[104:107], v[8:11]
	v_mfma_f32_16x16x32_bf16 v[24:27], v[108:111], v[130:133], v[24:27]
	v_mfma_f32_16x16x32_bf16 v[36:39], v[108:111], v[138:141], v[36:39]
	s_waitcnt vmcnt(6)
	v_mfma_f32_16x16x32_bf16 v[48:51], v[108:111], v[148:151], v[48:51]
	s_waitcnt vmcnt(2)
	v_mfma_f32_16x16x32_bf16 v[0:3], v[160:163], v[104:107], v[0:3]
	s_waitcnt vmcnt(0)
	v_mfma_f32_16x16x32_bf16 v[4:7], v[152:155], v[104:107], v[4:7]
	v_mfma_f32_16x16x32_bf16 v[12:15], v[156:159], v[104:107], v[12:15]
	v_mfma_f32_16x16x32_bf16 v[16:19], v[160:163], v[130:133], v[16:19]
	v_mfma_f32_16x16x32_bf16 v[20:23], v[152:155], v[130:133], v[20:23]
	v_mfma_f32_16x16x32_bf16 v[28:31], v[156:159], v[130:133], v[28:31]
	v_mfma_f32_16x16x32_bf16 v[32:35], v[160:163], v[138:141], v[32:35]
	v_mfma_f32_16x16x32_bf16 v[40:43], v[152:155], v[138:141], v[40:43]
	v_mfma_f32_16x16x32_bf16 v[44:47], v[156:159], v[138:141], v[44:47]
	v_mfma_f32_16x16x32_bf16 v[52:55], v[160:163], v[148:151], v[52:55]
	v_mfma_f32_16x16x32_bf16 v[56:59], v[152:155], v[148:151], v[56:59]
	v_mfma_f32_16x16x32_bf16 v[60:63], v[156:159], v[148:151], v[60:63]
	v_mfma_f32_16x16x32_bf16 v[8:11], v[164:167], v[168:171], v[8:11]
	v_mfma_f32_16x16x32_bf16 v[24:27], v[164:167], v[180:183], v[24:27]
	v_mfma_f32_16x16x32_bf16 v[36:39], v[164:167], v[184:187], v[36:39]
	v_mfma_f32_16x16x32_bf16 v[48:51], v[164:167], v[188:191], v[48:51]
	v_mfma_f32_16x16x32_bf16 v[0:3], v[192:195], v[168:171], v[0:3]
	v_mfma_f32_16x16x32_bf16 v[4:7], v[200:203], v[168:171], v[4:7]
	v_mfma_f32_16x16x32_bf16 v[12:15], v[208:211], v[168:171], v[12:15]
	v_mfma_f32_16x16x32_bf16 v[16:19], v[192:195], v[180:183], v[16:19]
	v_mfma_f32_16x16x32_bf16 v[20:23], v[200:203], v[180:183], v[20:23]
	v_mfma_f32_16x16x32_bf16 v[28:31], v[208:211], v[180:183], v[28:31]
	v_mfma_f32_16x16x32_bf16 v[32:35], v[192:195], v[184:187], v[32:35]
	v_mfma_f32_16x16x32_bf16 v[40:43], v[200:203], v[184:187], v[40:43]
	v_mfma_f32_16x16x32_bf16 v[44:47], v[208:211], v[184:187], v[44:47]
	v_mfma_f32_16x16x32_bf16 v[52:55], v[192:195], v[188:191], v[52:55]
	v_mfma_f32_16x16x32_bf16 v[56:59], v[200:203], v[188:191], v[56:59]
	v_mfma_f32_16x16x32_bf16 v[60:63], v[208:211], v[188:191], v[60:63]
	v_mfma_f32_16x16x32_bf16 v[8:11], v[176:179], v[172:175], v[8:11]
	v_mfma_f32_16x16x32_bf16 v[24:27], v[176:179], v[196:199], v[24:27]
	v_mfma_f32_16x16x32_bf16 v[36:39], v[176:179], v[204:207], v[36:39]
	v_mfma_f32_16x16x32_bf16 v[48:51], v[176:179], v[212:215], v[48:51]
	v_mfma_f32_16x16x32_bf16 v[0:3], v[220:223], v[172:175], v[0:3]
	v_mfma_f32_16x16x32_bf16 v[4:7], v[224:227], v[172:175], v[4:7]
	v_mfma_f32_16x16x32_bf16 v[12:15], v[216:219], v[172:175], v[12:15]
	v_mfma_f32_16x16x32_bf16 v[16:19], v[220:223], v[196:199], v[16:19]
	v_mfma_f32_16x16x32_bf16 v[20:23], v[224:227], v[196:199], v[20:23]
	v_mfma_f32_16x16x32_bf16 v[28:31], v[216:219], v[196:199], v[28:31]
	v_mfma_f32_16x16x32_bf16 v[32:35], v[220:223], v[204:207], v[32:35]
	v_mfma_f32_16x16x32_bf16 v[40:43], v[224:227], v[204:207], v[40:43]
	v_mfma_f32_16x16x32_bf16 v[44:47], v[216:219], v[204:207], v[44:47]
	v_mfma_f32_16x16x32_bf16 v[52:55], v[220:223], v[212:215], v[52:55]
	v_mfma_f32_16x16x32_bf16 v[56:59], v[224:227], v[212:215], v[56:59]
	v_mfma_f32_16x16x32_bf16 v[60:63], v[216:219], v[212:215], v[60:63]
	s_waitcnt lgkmcnt(0)
	s_barrier
	ds_write_b128 v91, v[8:11]
	ds_write_b128 v92, v[0:3]
	ds_write_b128 v93, v[4:7]
	ds_write_b128 v94, v[12:15]
	ds_write_b128 v91, v[24:27] offset:4096
	ds_write_b128 v92, v[16:19] offset:4096
	ds_write_b128 v93, v[20:23] offset:4096
	ds_write_b128 v94, v[28:31] offset:4096
	ds_write_b128 v91, v[36:39] offset:8192
	ds_write_b128 v92, v[32:35] offset:8192
	ds_write_b128 v93, v[40:43] offset:8192
	ds_write_b128 v94, v[44:47] offset:8192
	ds_write_b128 v91, v[48:51] offset:12288
	ds_write_b128 v92, v[52:55] offset:12288
	ds_write_b128 v93, v[56:59] offset:12288
	ds_write_b128 v94, v[60:63] offset:12288
	s_waitcnt lgkmcnt(0)
	s_barrier
	s_and_saveexec_b64 s[6:7], s[4:5]
	s_cbranch_execz .LBB0_1095
	ds_read_b128 v[0:3], v80
	ds_read_b128 v[4:7], v81
	ds_read_b128 v[8:11], v80 offset:16384
	ds_read_b128 v[12:15], v81 offset:16384
	v_mov_b32_e32 v71, v65
	s_waitcnt lgkmcnt(3)
	v_pk_add_f32 v[2:3], v[2:3], 0 op_sel_hi:[1,0]
	v_pk_add_f32 v[0:1], v[0:1], 0 op_sel_hi:[1,0]
	s_waitcnt lgkmcnt(1)
	v_pk_add_f32 v[16:17], v[2:3], v[10:11]
	v_pk_add_f32 v[18:19], v[0:1], v[8:9]
	ds_read_b128 v[0:3], v80 offset:32768
	v_pk_add_f32 v[6:7], v[6:7], 0 op_sel_hi:[1,0]
	v_pk_add_f32 v[4:5], v[4:5], 0 op_sel_hi:[1,0]
	s_waitcnt lgkmcnt(1)
	v_pk_add_f32 v[14:15], v[6:7], v[14:15]
	v_pk_add_f32 v[12:13], v[4:5], v[12:13]
	ds_read_b128 v[4:7], v81 offset:32768
	ds_read_b128 v[8:11], v80 offset:49152
	s_waitcnt lgkmcnt(2)
	v_pk_add_f32 v[16:17], v[16:17], v[2:3]
	v_pk_add_f32 v[18:19], v[18:19], v[0:1]
	ds_read_b128 v[0:3], v81 offset:49152
	s_waitcnt lgkmcnt(2)
	v_pk_add_f32 v[14:15], v[14:15], v[6:7]
	v_pk_add_f32 v[12:13], v[12:13], v[4:5]
	ds_read_b128 v[4:7], v82
	s_waitcnt lgkmcnt(2)
	v_pk_add_f32 v[16:17], v[16:17], v[10:11]
	v_pk_add_f32 v[18:19], v[18:19], v[8:9]
	s_waitcnt lgkmcnt(1)
	v_pk_add_f32 v[14:15], v[14:15], v[2:3]
	ds_read_b128 v[8:11], v83
	v_pk_add_f32 v[12:13], v[12:13], v[0:1]
	ds_read_b128 v[0:3], v84
	s_waitcnt lgkmcnt(2)
	v_pk_add_f32 v[16:17], v[16:17], v[6:7]
	v_pk_add_f32 v[24:25], v[18:19], v[4:5]
	ds_read_b128 v[4:7], v85
	s_waitcnt lgkmcnt(2)
	v_pk_add_f32 v[26:27], v[14:15], v[10:11]
	v_pk_add_f32 v[28:29], v[12:13], v[8:9]
	s_waitcnt lgkmcnt(1)
	v_pk_add_f32 v[2:3], v[16:17], v[2:3]
	ds_read_b128 v[8:11], v86
	ds_read_b128 v[12:15], v87
	ds_read_b128 v[16:19], v88
	ds_read_b128 v[20:23], v89
	s_waitcnt lgkmcnt(4)
	v_pk_add_f32 v[4:5], v[28:29], v[4:5]
	v_pk_add_f32 v[0:1], v[24:25], v[0:1]
	s_waitcnt lgkmcnt(2)
	v_pk_add_f32 v[4:5], v[4:5], v[12:13]
	v_pk_add_f32 v[0:1], v[0:1], v[8:9]
	s_waitcnt lgkmcnt(0)
	v_pk_add_f32 v[4:5], v[4:5], v[20:21]
	v_pk_add_f32 v[0:1], v[0:1], v[16:17]
	v_mul_f32_e32 v4, 0xbfb8aa3b, v4
	v_mul_f32_e32 v5, 0xbfb8aa3b, v5
	v_exp_f32_e32 v4, v4
	v_exp_f32_e32 v5, v5
	v_pk_add_f32 v[2:3], v[2:3], v[10:11]
	v_pk_add_f32 v[6:7], v[26:27], v[6:7]
	v_pk_add_f32 v[2:3], v[2:3], v[18:19]
	v_pk_add_f32 v[4:5], v[4:5], 1.0 op_sel_hi:[1,0]
	v_pk_add_f32 v[6:7], v[6:7], v[14:15]
	v_div_scale_f32 v8, s[8:9], v5, v5, v1
	v_rcp_f32_e32 v9, v8
	v_pk_add_f32 v[6:7], v[6:7], v[22:23]
	v_fma_f32 v10, -v8, v9, 1.0
	v_fmac_f32_e32 v9, v10, v9
	v_div_scale_f32 v10, vcc, v1, v5, v1
	v_mul_f32_e32 v11, v10, v9
	v_fma_f32 v12, -v8, v11, v10
	v_fmac_f32_e32 v11, v12, v9
	v_fma_f32 v8, -v8, v11, v10
	v_div_scale_f32 v10, s[8:9], v4, v4, v0
	v_rcp_f32_e32 v12, v10
	v_mul_f32_e32 v6, 0xbfb8aa3b, v6
	v_mul_f32_e32 v7, 0xbfb8aa3b, v7
	v_div_fmas_f32 v8, v8, v9, v11
	v_exp_f32_e32 v6, v6
	v_exp_f32_e32 v7, v7
	v_div_fixup_f32 v1, v8, v5, v1
	v_fma_f32 v5, -v10, v12, 1.0
	v_fmac_f32_e32 v12, v5, v12
	v_div_scale_f32 v5, vcc, v0, v4, v0
	v_mul_f32_e32 v8, v5, v12
	v_fma_f32 v9, -v10, v8, v5
	v_pk_add_f32 v[6:7], v[6:7], 1.0 op_sel_hi:[1,0]
	v_fmac_f32_e32 v8, v9, v12
	v_div_scale_f32 v9, s[8:9], v7, v7, v3
	v_fma_f32 v5, -v10, v8, v5
	v_rcp_f32_e32 v10, v9
	v_div_fmas_f32 v5, v5, v12, v8
	v_div_fixup_f32 v0, v5, v4, v0
	v_cvt_pk_bf16_f32 v0, v0, v1
	v_fma_f32 v4, -v9, v10, 1.0
	v_fmac_f32_e32 v10, v4, v10
	v_div_scale_f32 v4, vcc, v3, v7, v3
	v_mul_f32_e32 v5, v4, v10
	v_fma_f32 v8, -v9, v5, v4
	v_fmac_f32_e32 v5, v8, v10
	v_div_scale_f32 v8, s[8:9], v6, v6, v2
	v_fma_f32 v4, -v9, v5, v4
	v_rcp_f32_e32 v9, v8
	v_div_fmas_f32 v4, v4, v10, v5
	v_div_fixup_f32 v3, v4, v7, v3
	v_fma_f32 v4, -v8, v9, 1.0
	v_fmac_f32_e32 v9, v4, v9
	v_div_scale_f32 v4, vcc, v2, v6, v2
	v_mul_f32_e32 v5, v4, v9
	v_fma_f32 v7, -v8, v5, v4
	v_fmac_f32_e32 v5, v7, v9
	v_fma_f32 v4, -v8, v5, v4
	v_div_fmas_f32 v4, v4, v9, v5
	v_div_fixup_f32 v2, v4, v6, v2
	v_cvt_pk_bf16_f32 v1, v2, v3
	v_or_b32_e32 v2, s15, v78
	v_lshlrev_b32_e32 v64, 11, v2
	v_lshl_add_u64 v[2:3], s[46:47], 0, v[64:65]
	v_lshl_or_b32 v64, s14, 6, v95
	v_lshl_add_u64 v[2:3], v[2:3], 0, v[64:65]
	v_lshl_add_u64 v[2:3], v[2:3], 0, v[70:71]
	global_store_dwordx2 v[2:3], v[0:1], off
	s_branch .LBB0_1095

.LBB0_1125:
	s_lshl_b64 s[8:9], s[8:9], 1
	v_lshl_add_u64 v[108:109], v[72:73], 0, s[8:9]
	v_add_co_u32_e32 v124, vcc, s12, v108
	v_lshl_add_u64 v[110:111], v[74:75], 0, s[8:9]
	s_nop 0
	v_addc_co_u32_e32 v125, vcc, 0, v109, vcc
	v_add_co_u32_e32 v134, vcc, s10, v108
	global_load_dwordx4 v[164:167], v[110:111], off offset:128
	global_load_dwordx4 v[96:99], v[110:111], off
	s_nop 0
	v_addc_co_u32_e32 v135, vcc, 0, v109, vcc
	v_add_co_u32_e32 v144, vcc, s11, v108
	global_load_dwordx4 v[168:171], v[108:109], off offset:128
	global_load_dwordx4 v[92:95], v[108:109], off
	s_nop 0
	v_addc_co_u32_e32 v145, vcc, 0, v109, vcc
	v_add_co_u32_e32 v152, vcc, s12, v110
	s_mov_b64 s[8:9], 64
	s_nop 0
	v_addc_co_u32_e32 v153, vcc, 0, v111, vcc
	v_add_co_u32_e32 v154, vcc, s10, v110
	s_nop 1
	v_addc_co_u32_e32 v155, vcc, 0, v111, vcc
	v_add_co_u32_e32 v156, vcc, s11, v110
	s_nop 1
	v_addc_co_u32_e32 v157, vcc, 0, v111, vcc
	global_load_dwordx4 v[172:175], v[108:109], off offset:192
	global_load_dwordx4 v[100:103], v[108:109], off offset:64
	global_load_dwordx4 v[176:179], v[110:111], off offset:192
	global_load_dwordx4 v[104:107], v[110:111], off offset:64
	s_nop 0
	global_load_dwordx4 v[180:183], v[124:125], off offset:128
	global_load_dwordx4 v[108:111], v[124:125], off
	global_load_dwordx4 v[184:187], v[134:135], off offset:128
	global_load_dwordx4 v[112:115], v[134:135], off
	global_load_dwordx4 v[188:191], v[144:145], off offset:128
	global_load_dwordx4 v[116:119], v[144:145], off
	global_load_dwordx4 v[192:195], v[152:153], off offset:128
	global_load_dwordx4 v[120:123], v[152:153], off
	s_nop 0
	global_load_dwordx4 v[196:199], v[124:125], off offset:192
	global_load_dwordx4 v[124:127], v[124:125], off offset:64
	global_load_dwordx4 v[200:203], v[154:155], off offset:128
	global_load_dwordx4 v[130:133], v[154:155], off
	s_nop 0
	global_load_dwordx4 v[204:207], v[134:135], off offset:192
	global_load_dwordx4 v[134:137], v[134:135], off offset:64
	s_nop 0
	global_load_dwordx4 v[208:211], v[156:157], off offset:128
	global_load_dwordx4 v[138:141], v[156:157], off
	global_load_dwordx4 v[212:215], v[144:145], off offset:192
	global_load_dwordx4 v[148:151], v[144:145], off offset:64
	s_andn2_b64 vcc, exec, s[6:7]
	global_load_dwordx4 v[216:219], v[156:157], off offset:192
	global_load_dwordx4 v[156:159], v[156:157], off offset:64
	s_mov_b64 s[6:7], 0
	global_load_dwordx4 v[220:223], v[152:153], off offset:192
	global_load_dwordx4 v[160:163], v[152:153], off offset:64
	s_nop 0
	global_load_dwordx4 v[224:227], v[154:155], off offset:192
	global_load_dwordx4 v[152:155], v[154:155], off offset:64
	s_waitcnt vmcnt(28)
	v_mfma_f32_16x16x32_bf16 v[8:11], v[96:99], v[92:95], v[8:11]
	s_waitcnt vmcnt(22)
	v_mfma_f32_16x16x32_bf16 v[24:27], v[96:99], v[108:111], v[24:27]
	s_waitcnt vmcnt(20)
	v_mfma_f32_16x16x32_bf16 v[36:39], v[96:99], v[112:115], v[36:39]
	s_waitcnt vmcnt(18)
	v_mfma_f32_16x16x32_bf16 v[48:51], v[96:99], v[116:119], v[48:51]
	s_waitcnt vmcnt(16)
	v_mfma_f32_16x16x32_bf16 v[0:3], v[120:123], v[92:95], v[0:3]
	s_waitcnt vmcnt(12)
	v_mfma_f32_16x16x32_bf16 v[4:7], v[130:133], v[92:95], v[4:7]
	s_waitcnt vmcnt(8)
	v_mfma_f32_16x16x32_bf16 v[12:15], v[138:141], v[92:95], v[12:15]
	v_mfma_f32_16x16x32_bf16 v[16:19], v[120:123], v[108:111], v[16:19]
	v_mfma_f32_16x16x32_bf16 v[20:23], v[130:133], v[108:111], v[20:23]
	v_mfma_f32_16x16x32_bf16 v[28:31], v[138:141], v[108:111], v[28:31]
	v_mfma_f32_16x16x32_bf16 v[32:35], v[120:123], v[112:115], v[32:35]
	v_mfma_f32_16x16x32_bf16 v[40:43], v[130:133], v[112:115], v[40:43]
	v_mfma_f32_16x16x32_bf16 v[44:47], v[138:141], v[112:115], v[44:47]
	v_mfma_f32_16x16x32_bf16 v[52:55], v[120:123], v[116:119], v[52:55]
	v_mfma_f32_16x16x32_bf16 v[56:59], v[130:133], v[116:119], v[56:59]
	v_mfma_f32_16x16x32_bf16 v[60:63], v[138:141], v[116:119], v[60:63]
	v_mfma_f32_16x16x32_bf16 v[8:11], v[104:107], v[100:103], v[8:11]
	v_mfma_f32_16x16x32_bf16 v[24:27], v[104:107], v[124:127], v[24:27]
	v_mfma_f32_16x16x32_bf16 v[36:39], v[104:107], v[134:137], v[36:39]
	s_waitcnt vmcnt(6)
	v_mfma_f32_16x16x32_bf16 v[48:51], v[104:107], v[148:151], v[48:51]
	s_waitcnt vmcnt(2)
	v_mfma_f32_16x16x32_bf16 v[0:3], v[160:163], v[100:103], v[0:3]
	s_waitcnt vmcnt(0)
	v_mfma_f32_16x16x32_bf16 v[4:7], v[152:155], v[100:103], v[4:7]
	v_mfma_f32_16x16x32_bf16 v[12:15], v[156:159], v[100:103], v[12:15]
	v_mfma_f32_16x16x32_bf16 v[16:19], v[160:163], v[124:127], v[16:19]
	v_mfma_f32_16x16x32_bf16 v[20:23], v[152:155], v[124:127], v[20:23]
	v_mfma_f32_16x16x32_bf16 v[28:31], v[156:159], v[124:127], v[28:31]
	v_mfma_f32_16x16x32_bf16 v[32:35], v[160:163], v[134:137], v[32:35]
	v_mfma_f32_16x16x32_bf16 v[40:43], v[152:155], v[134:137], v[40:43]
	v_mfma_f32_16x16x32_bf16 v[44:47], v[156:159], v[134:137], v[44:47]
	v_mfma_f32_16x16x32_bf16 v[52:55], v[160:163], v[148:151], v[52:55]
	v_mfma_f32_16x16x32_bf16 v[56:59], v[152:155], v[148:151], v[56:59]
	v_mfma_f32_16x16x32_bf16 v[60:63], v[156:159], v[148:151], v[60:63]
	v_mfma_f32_16x16x32_bf16 v[8:11], v[164:167], v[168:171], v[8:11]
	v_mfma_f32_16x16x32_bf16 v[24:27], v[164:167], v[180:183], v[24:27]
	v_mfma_f32_16x16x32_bf16 v[36:39], v[164:167], v[184:187], v[36:39]
	v_mfma_f32_16x16x32_bf16 v[48:51], v[164:167], v[188:191], v[48:51]
	v_mfma_f32_16x16x32_bf16 v[0:3], v[192:195], v[168:171], v[0:3]
	v_mfma_f32_16x16x32_bf16 v[4:7], v[200:203], v[168:171], v[4:7]
	v_mfma_f32_16x16x32_bf16 v[12:15], v[208:211], v[168:171], v[12:15]
	v_mfma_f32_16x16x32_bf16 v[16:19], v[192:195], v[180:183], v[16:19]
	v_mfma_f32_16x16x32_bf16 v[20:23], v[200:203], v[180:183], v[20:23]
	v_mfma_f32_16x16x32_bf16 v[28:31], v[208:211], v[180:183], v[28:31]
	v_mfma_f32_16x16x32_bf16 v[32:35], v[192:195], v[184:187], v[32:35]
	v_mfma_f32_16x16x32_bf16 v[40:43], v[200:203], v[184:187], v[40:43]
	v_mfma_f32_16x16x32_bf16 v[44:47], v[208:211], v[184:187], v[44:47]
	v_mfma_f32_16x16x32_bf16 v[52:55], v[192:195], v[188:191], v[52:55]
	v_mfma_f32_16x16x32_bf16 v[56:59], v[200:203], v[188:191], v[56:59]
	v_mfma_f32_16x16x32_bf16 v[60:63], v[208:211], v[188:191], v[60:63]
	v_mfma_f32_16x16x32_bf16 v[8:11], v[176:179], v[172:175], v[8:11]
	v_mfma_f32_16x16x32_bf16 v[24:27], v[176:179], v[196:199], v[24:27]
	v_mfma_f32_16x16x32_bf16 v[36:39], v[176:179], v[204:207], v[36:39]
	v_mfma_f32_16x16x32_bf16 v[48:51], v[176:179], v[212:215], v[48:51]
	v_mfma_f32_16x16x32_bf16 v[0:3], v[220:223], v[172:175], v[0:3]
	v_mfma_f32_16x16x32_bf16 v[4:7], v[224:227], v[172:175], v[4:7]
	v_mfma_f32_16x16x32_bf16 v[12:15], v[216:219], v[172:175], v[12:15]
	v_mfma_f32_16x16x32_bf16 v[16:19], v[220:223], v[196:199], v[16:19]
	v_mfma_f32_16x16x32_bf16 v[20:23], v[224:227], v[196:199], v[20:23]
	v_mfma_f32_16x16x32_bf16 v[28:31], v[216:219], v[196:199], v[28:31]
	v_mfma_f32_16x16x32_bf16 v[32:35], v[220:223], v[204:207], v[32:35]
	v_mfma_f32_16x16x32_bf16 v[40:43], v[224:227], v[204:207], v[40:43]
	v_mfma_f32_16x16x32_bf16 v[44:47], v[216:219], v[204:207], v[44:47]
	v_mfma_f32_16x16x32_bf16 v[52:55], v[220:223], v[212:215], v[52:55]
	v_mfma_f32_16x16x32_bf16 v[56:59], v[224:227], v[212:215], v[56:59]
	v_mfma_f32_16x16x32_bf16 v[60:63], v[216:219], v[212:215], v[60:63]
	s_waitcnt lgkmcnt(0)
	s_barrier
	ds_write_b128 v87, v[8:11]
	ds_write_b128 v88, v[0:3]
	ds_write_b128 v89, v[4:7]
	ds_write_b128 v90, v[12:15]
	ds_write_b128 v87, v[24:27] offset:4096
	ds_write_b128 v88, v[16:19] offset:4096
	ds_write_b128 v89, v[20:23] offset:4096
	ds_write_b128 v90, v[28:31] offset:4096
	ds_write_b128 v87, v[36:39] offset:8192
	ds_write_b128 v88, v[32:35] offset:8192
	ds_write_b128 v89, v[40:43] offset:8192
	ds_write_b128 v90, v[44:47] offset:8192
	ds_write_b128 v87, v[48:51] offset:12288
	ds_write_b128 v88, v[52:55] offset:12288
	ds_write_b128 v89, v[56:59] offset:12288
	ds_write_b128 v90, v[60:63] offset:12288
	s_waitcnt lgkmcnt(0)
	s_barrier
	s_and_saveexec_b64 s[6:7], s[4:5]
	s_cbranch_execz .LBB0_1123
	ds_read_b128 v[0:3], v76
	ds_read_b128 v[4:7], v77
	ds_read_b128 v[8:11], v76 offset:16384
	ds_read_b128 v[12:15], v77 offset:16384
	v_mov_b32_e32 v71, v65
	s_waitcnt lgkmcnt(3)
	v_pk_add_f32 v[2:3], v[2:3], 0 op_sel_hi:[1,0]
	v_pk_add_f32 v[0:1], v[0:1], 0 op_sel_hi:[1,0]
	s_waitcnt lgkmcnt(1)
	v_pk_add_f32 v[16:17], v[2:3], v[10:11]
	v_pk_add_f32 v[18:19], v[0:1], v[8:9]
	ds_read_b128 v[0:3], v76 offset:32768
	v_pk_add_f32 v[6:7], v[6:7], 0 op_sel_hi:[1,0]
	v_pk_add_f32 v[4:5], v[4:5], 0 op_sel_hi:[1,0]
	s_waitcnt lgkmcnt(1)
	v_pk_add_f32 v[14:15], v[6:7], v[14:15]
	v_pk_add_f32 v[12:13], v[4:5], v[12:13]
	ds_read_b128 v[4:7], v77 offset:32768
	ds_read_b128 v[8:11], v76 offset:49152
	s_waitcnt lgkmcnt(2)
	v_pk_add_f32 v[16:17], v[16:17], v[2:3]
	v_pk_add_f32 v[18:19], v[18:19], v[0:1]
	ds_read_b128 v[0:3], v77 offset:49152
	s_waitcnt lgkmcnt(2)
	v_pk_add_f32 v[14:15], v[14:15], v[6:7]
	v_pk_add_f32 v[12:13], v[12:13], v[4:5]
	ds_read_b128 v[4:7], v78
	s_waitcnt lgkmcnt(2)
	v_pk_add_f32 v[16:17], v[16:17], v[10:11]
	v_pk_add_f32 v[18:19], v[18:19], v[8:9]
	s_waitcnt lgkmcnt(1)
	v_pk_add_f32 v[14:15], v[14:15], v[2:3]
	ds_read_b128 v[8:11], v79
	v_pk_add_f32 v[12:13], v[12:13], v[0:1]
	ds_read_b128 v[0:3], v80
	s_waitcnt lgkmcnt(2)
	v_pk_add_f32 v[16:17], v[16:17], v[6:7]
	v_pk_add_f32 v[24:25], v[18:19], v[4:5]
	ds_read_b128 v[4:7], v81
	s_waitcnt lgkmcnt(2)
	v_pk_add_f32 v[26:27], v[14:15], v[10:11]
	v_pk_add_f32 v[28:29], v[12:13], v[8:9]
	s_waitcnt lgkmcnt(1)
	v_pk_add_f32 v[2:3], v[16:17], v[2:3]
	ds_read_b128 v[8:11], v82
	ds_read_b128 v[12:15], v83
	ds_read_b128 v[16:19], v84
	ds_read_b128 v[20:23], v85
	s_waitcnt lgkmcnt(4)
	v_pk_add_f32 v[4:5], v[28:29], v[4:5]
	v_pk_add_f32 v[0:1], v[24:25], v[0:1]
	s_waitcnt lgkmcnt(2)
	v_pk_add_f32 v[4:5], v[4:5], v[12:13]
	v_pk_add_f32 v[0:1], v[0:1], v[8:9]
	s_waitcnt lgkmcnt(0)
	v_pk_add_f32 v[4:5], v[4:5], v[20:21]
	v_pk_add_f32 v[0:1], v[0:1], v[16:17]
	v_mul_f32_e32 v4, 0xbfb8aa3b, v4
	v_mul_f32_e32 v5, 0xbfb8aa3b, v5
	v_exp_f32_e32 v4, v4
	v_exp_f32_e32 v5, v5
	v_pk_add_f32 v[2:3], v[2:3], v[10:11]
	v_pk_add_f32 v[6:7], v[26:27], v[6:7]
	v_pk_add_f32 v[2:3], v[2:3], v[18:19]
	v_pk_add_f32 v[4:5], v[4:5], 1.0 op_sel_hi:[1,0]
	v_pk_add_f32 v[6:7], v[6:7], v[14:15]
	v_div_scale_f32 v8, s[8:9], v5, v5, v1
	v_rcp_f32_e32 v9, v8
	v_pk_add_f32 v[6:7], v[6:7], v[22:23]
	v_fma_f32 v10, -v8, v9, 1.0
	v_fmac_f32_e32 v9, v10, v9
	v_div_scale_f32 v10, vcc, v1, v5, v1
	v_mul_f32_e32 v11, v10, v9
	v_fma_f32 v12, -v8, v11, v10
	v_fmac_f32_e32 v11, v12, v9
	v_fma_f32 v8, -v8, v11, v10
	v_div_scale_f32 v10, s[8:9], v4, v4, v0
	v_rcp_f32_e32 v12, v10
	v_mul_f32_e32 v6, 0xbfb8aa3b, v6
	v_mul_f32_e32 v7, 0xbfb8aa3b, v7
	v_div_fmas_f32 v8, v8, v9, v11
	v_exp_f32_e32 v6, v6
	v_exp_f32_e32 v7, v7
	v_div_fixup_f32 v1, v8, v5, v1
	v_fma_f32 v5, -v10, v12, 1.0
	v_fmac_f32_e32 v12, v5, v12
	v_div_scale_f32 v5, vcc, v0, v4, v0
	v_mul_f32_e32 v8, v5, v12
	v_fma_f32 v9, -v10, v8, v5
	v_pk_add_f32 v[6:7], v[6:7], 1.0 op_sel_hi:[1,0]
	v_fmac_f32_e32 v8, v9, v12
	v_div_scale_f32 v9, s[8:9], v7, v7, v3
	v_fma_f32 v5, -v10, v8, v5
	v_rcp_f32_e32 v10, v9
	v_div_fmas_f32 v5, v5, v12, v8
	v_div_fixup_f32 v0, v5, v4, v0
	v_cvt_pk_bf16_f32 v0, v0, v1
	v_fma_f32 v4, -v9, v10, 1.0
	v_fmac_f32_e32 v10, v4, v10
	v_div_scale_f32 v4, vcc, v3, v7, v3
	v_mul_f32_e32 v5, v4, v10
	v_fma_f32 v8, -v9, v5, v4
	v_fmac_f32_e32 v5, v8, v10
	v_div_scale_f32 v8, s[8:9], v6, v6, v2
	v_fma_f32 v4, -v9, v5, v4
	v_rcp_f32_e32 v9, v8
	v_div_fmas_f32 v4, v4, v10, v5
	v_div_fixup_f32 v3, v4, v7, v3
	v_fma_f32 v4, -v8, v9, 1.0
	v_fmac_f32_e32 v9, v4, v9
	v_div_scale_f32 v4, vcc, v2, v6, v2
	v_mul_f32_e32 v5, v4, v9
	v_fma_f32 v7, -v8, v5, v4
	v_fmac_f32_e32 v5, v7, v9
	v_fma_f32 v4, -v8, v5, v4
	v_div_fmas_f32 v4, v4, v9, v5
	v_div_fixup_f32 v2, v4, v6, v2
	v_cvt_pk_bf16_f32 v1, v2, v3
	v_or_b32_e32 v2, s15, v142
	v_lshlrev_b32_e32 v64, 11, v2
	v_lshl_add_u64 v[2:3], s[46:47], 0, v[64:65]
	v_lshl_or_b32 v64, s14, 6, v91
	v_lshl_add_u64 v[2:3], v[2:3], 0, v[64:65]
	v_lshl_add_u64 v[2:3], v[2:3], 0, v[70:71]
	global_store_dwordx2 v[2:3], v[0:1], off
	s_branch .LBB0_1123

.LBB0_1268:
	s_lshl_b64 s[10:11], s[10:11], 1
	v_lshl_add_u64 v[108:109], v[70:71], 0, s[10:11]
	v_add_co_u32_e32 v116, vcc, s16, v108
	v_lshl_add_u64 v[110:111], v[72:73], 0, s[10:11]
	s_nop 0
	v_addc_co_u32_e32 v117, vcc, 0, v109, vcc
	v_add_co_u32_e32 v124, vcc, s17, v108
	global_load_dwordx4 v[164:167], v[110:111], off offset:128
	global_load_dwordx4 v[88:91], v[110:111], off
	s_nop 0
	v_addc_co_u32_e32 v125, vcc, 0, v109, vcc
	v_add_co_u32_e32 v134, vcc, s18, v108
	global_load_dwordx4 v[168:171], v[108:109], off offset:128
	global_load_dwordx4 v[84:87], v[108:109], off
	s_nop 0
	v_addc_co_u32_e32 v135, vcc, 0, v109, vcc
	v_add_co_u32_e32 v138, vcc, s16, v110
	s_mov_b64 s[10:11], 64
	s_nop 0
	v_addc_co_u32_e32 v139, vcc, 0, v111, vcc
	v_add_co_u32_e32 v140, vcc, s17, v110
	s_nop 1
	v_addc_co_u32_e32 v141, vcc, 0, v111, vcc
	v_add_co_u32_e32 v142, vcc, s18, v110
	s_nop 1
	v_addc_co_u32_e32 v143, vcc, 0, v111, vcc
	global_load_dwordx4 v[172:175], v[108:109], off offset:192
	global_load_dwordx4 v[92:95], v[108:109], off offset:64
	global_load_dwordx4 v[176:179], v[110:111], off offset:192
	global_load_dwordx4 v[96:99], v[110:111], off offset:64
	global_load_dwordx4 v[180:183], v[116:117], off offset:128
	global_load_dwordx4 v[100:103], v[116:117], off
	global_load_dwordx4 v[184:187], v[124:125], off offset:128
	global_load_dwordx4 v[104:107], v[124:125], off
	s_nop 0
	global_load_dwordx4 v[188:191], v[134:135], off offset:128
	global_load_dwordx4 v[108:111], v[134:135], off
	global_load_dwordx4 v[192:195], v[138:139], off offset:128
	global_load_dwordx4 v[112:115], v[138:139], off
	s_nop 0
	global_load_dwordx4 v[196:199], v[116:117], off offset:192
	global_load_dwordx4 v[116:119], v[116:117], off offset:64
	global_load_dwordx4 v[200:203], v[140:141], off offset:128
	global_load_dwordx4 v[120:123], v[140:141], off
	s_nop 0
	global_load_dwordx4 v[204:207], v[124:125], off offset:192
	global_load_dwordx4 v[124:127], v[124:125], off offset:64
	s_nop 0
	global_load_dwordx4 v[208:211], v[142:143], off offset:128
	global_load_dwordx4 v[130:133], v[142:143], off
	s_nop 0
	global_load_dwordx4 v[212:215], v[134:135], off offset:192
	global_load_dwordx4 v[134:137], v[134:135], off offset:64
	s_andn2_b64 vcc, exec, s[8:9]
	global_load_dwordx4 v[216:219], v[142:143], off offset:192
	global_load_dwordx4 v[142:145], v[142:143], off offset:64
	s_mov_b64 s[8:9], 0
	global_load_dwordx4 v[220:223], v[138:139], off offset:192
	global_load_dwordx4 v[160:163], v[138:139], off offset:64
	s_nop 0
	global_load_dwordx4 v[224:227], v[140:141], off offset:192
	global_load_dwordx4 v[138:141], v[140:141], off offset:64
	s_waitcnt vmcnt(28)
	v_mfma_f32_16x16x32_bf16 v[8:11], v[88:91], v[84:87], v[8:11]
	s_waitcnt vmcnt(22)
	v_mfma_f32_16x16x32_bf16 v[24:27], v[88:91], v[100:103], v[24:27]
	s_waitcnt vmcnt(20)
	v_mfma_f32_16x16x32_bf16 v[36:39], v[88:91], v[104:107], v[36:39]
	s_waitcnt vmcnt(18)
	v_mfma_f32_16x16x32_bf16 v[48:51], v[88:91], v[108:111], v[48:51]
	s_waitcnt vmcnt(16)
	v_mfma_f32_16x16x32_bf16 v[0:3], v[112:115], v[84:87], v[0:3]
	s_waitcnt vmcnt(12)
	v_mfma_f32_16x16x32_bf16 v[4:7], v[120:123], v[84:87], v[4:7]
	s_waitcnt vmcnt(8)
	v_mfma_f32_16x16x32_bf16 v[12:15], v[130:133], v[84:87], v[12:15]
	v_mfma_f32_16x16x32_bf16 v[16:19], v[112:115], v[100:103], v[16:19]
	v_mfma_f32_16x16x32_bf16 v[20:23], v[120:123], v[100:103], v[20:23]
	v_mfma_f32_16x16x32_bf16 v[28:31], v[130:133], v[100:103], v[28:31]
	v_mfma_f32_16x16x32_bf16 v[32:35], v[112:115], v[104:107], v[32:35]
	v_mfma_f32_16x16x32_bf16 v[40:43], v[120:123], v[104:107], v[40:43]
	v_mfma_f32_16x16x32_bf16 v[44:47], v[130:133], v[104:107], v[44:47]
	v_mfma_f32_16x16x32_bf16 v[52:55], v[112:115], v[108:111], v[52:55]
	v_mfma_f32_16x16x32_bf16 v[56:59], v[120:123], v[108:111], v[56:59]
	v_mfma_f32_16x16x32_bf16 v[60:63], v[130:133], v[108:111], v[60:63]
	v_mfma_f32_16x16x32_bf16 v[8:11], v[96:99], v[92:95], v[8:11]
	v_mfma_f32_16x16x32_bf16 v[24:27], v[96:99], v[116:119], v[24:27]
	v_mfma_f32_16x16x32_bf16 v[36:39], v[96:99], v[124:127], v[36:39]
	s_waitcnt vmcnt(6)
	v_mfma_f32_16x16x32_bf16 v[48:51], v[96:99], v[134:137], v[48:51]
	s_waitcnt vmcnt(2)
	v_mfma_f32_16x16x32_bf16 v[0:3], v[160:163], v[92:95], v[0:3]
	s_waitcnt vmcnt(0)
	v_mfma_f32_16x16x32_bf16 v[4:7], v[138:141], v[92:95], v[4:7]
	v_mfma_f32_16x16x32_bf16 v[12:15], v[142:145], v[92:95], v[12:15]
	v_mfma_f32_16x16x32_bf16 v[16:19], v[160:163], v[116:119], v[16:19]
	v_mfma_f32_16x16x32_bf16 v[20:23], v[138:141], v[116:119], v[20:23]
	v_mfma_f32_16x16x32_bf16 v[28:31], v[142:145], v[116:119], v[28:31]
	v_mfma_f32_16x16x32_bf16 v[32:35], v[160:163], v[124:127], v[32:35]
	v_mfma_f32_16x16x32_bf16 v[40:43], v[138:141], v[124:127], v[40:43]
	v_mfma_f32_16x16x32_bf16 v[44:47], v[142:145], v[124:127], v[44:47]
	v_mfma_f32_16x16x32_bf16 v[52:55], v[160:163], v[134:137], v[52:55]
	v_mfma_f32_16x16x32_bf16 v[56:59], v[138:141], v[134:137], v[56:59]
	v_mfma_f32_16x16x32_bf16 v[60:63], v[142:145], v[134:137], v[60:63]
	v_mfma_f32_16x16x32_bf16 v[8:11], v[164:167], v[168:171], v[8:11]
	v_mfma_f32_16x16x32_bf16 v[24:27], v[164:167], v[180:183], v[24:27]
	v_mfma_f32_16x16x32_bf16 v[36:39], v[164:167], v[184:187], v[36:39]
	v_mfma_f32_16x16x32_bf16 v[48:51], v[164:167], v[188:191], v[48:51]
	v_mfma_f32_16x16x32_bf16 v[0:3], v[192:195], v[168:171], v[0:3]
	v_mfma_f32_16x16x32_bf16 v[4:7], v[200:203], v[168:171], v[4:7]
	v_mfma_f32_16x16x32_bf16 v[12:15], v[208:211], v[168:171], v[12:15]
	v_mfma_f32_16x16x32_bf16 v[16:19], v[192:195], v[180:183], v[16:19]
	v_mfma_f32_16x16x32_bf16 v[20:23], v[200:203], v[180:183], v[20:23]
	v_mfma_f32_16x16x32_bf16 v[28:31], v[208:211], v[180:183], v[28:31]
	v_mfma_f32_16x16x32_bf16 v[32:35], v[192:195], v[184:187], v[32:35]
	v_mfma_f32_16x16x32_bf16 v[40:43], v[200:203], v[184:187], v[40:43]
	v_mfma_f32_16x16x32_bf16 v[44:47], v[208:211], v[184:187], v[44:47]
	v_mfma_f32_16x16x32_bf16 v[52:55], v[192:195], v[188:191], v[52:55]
	v_mfma_f32_16x16x32_bf16 v[56:59], v[200:203], v[188:191], v[56:59]
	v_mfma_f32_16x16x32_bf16 v[60:63], v[208:211], v[188:191], v[60:63]
	v_mfma_f32_16x16x32_bf16 v[8:11], v[176:179], v[172:175], v[8:11]
	v_mfma_f32_16x16x32_bf16 v[24:27], v[176:179], v[196:199], v[24:27]
	v_mfma_f32_16x16x32_bf16 v[36:39], v[176:179], v[204:207], v[36:39]
	v_mfma_f32_16x16x32_bf16 v[48:51], v[176:179], v[212:215], v[48:51]
	v_mfma_f32_16x16x32_bf16 v[0:3], v[220:223], v[172:175], v[0:3]
	v_mfma_f32_16x16x32_bf16 v[4:7], v[224:227], v[172:175], v[4:7]
	v_mfma_f32_16x16x32_bf16 v[12:15], v[216:219], v[172:175], v[12:15]
	v_mfma_f32_16x16x32_bf16 v[16:19], v[220:223], v[196:199], v[16:19]
	v_mfma_f32_16x16x32_bf16 v[20:23], v[224:227], v[196:199], v[20:23]
	v_mfma_f32_16x16x32_bf16 v[28:31], v[216:219], v[196:199], v[28:31]
	v_mfma_f32_16x16x32_bf16 v[32:35], v[220:223], v[204:207], v[32:35]
	v_mfma_f32_16x16x32_bf16 v[40:43], v[224:227], v[204:207], v[40:43]
	v_mfma_f32_16x16x32_bf16 v[44:47], v[216:219], v[204:207], v[44:47]
	v_mfma_f32_16x16x32_bf16 v[52:55], v[220:223], v[212:215], v[52:55]
	v_mfma_f32_16x16x32_bf16 v[56:59], v[224:227], v[212:215], v[56:59]
	v_mfma_f32_16x16x32_bf16 v[60:63], v[216:219], v[212:215], v[60:63]
	s_lshl_b32 s8, s12, 12
	s_and_b32 s8, s8, 0x1c0000
	s_and_b32 s9, s14, 0xfc0
	s_or_b32 s8, s9, s8
	v_add_lshl_u32 v64, s8, v76, 1
	v_lshl_add_u64 v[70:71], s[46:47], 0, v[64:65]
	s_barrier
	ds_write_b128 v80, v[8:11]
	ds_write_b128 v81, v[0:3]
	ds_write_b128 v82, v[4:7]
	ds_write_b128 v83, v[12:15]
	ds_write_b128 v80, v[24:27] offset:4096
	ds_write_b128 v81, v[16:19] offset:4096
	ds_write_b128 v82, v[20:23] offset:4096
	ds_write_b128 v83, v[28:31] offset:4096
	ds_write_b128 v80, v[36:39] offset:8192
	ds_write_b128 v81, v[32:35] offset:8192
	ds_write_b128 v82, v[40:43] offset:8192
	ds_write_b128 v83, v[44:47] offset:8192
	ds_write_b128 v80, v[48:51] offset:12288
	ds_write_b128 v81, v[52:55] offset:12288
	ds_write_b128 v82, v[56:59] offset:12288
	ds_write_b128 v83, v[60:63] offset:12288
	s_mov_b64 s[8:9], 0
	v_mov_b32_e32 v0, v78
	v_mov_b32_e32 v1, v77
	v_mov_b32_e32 v2, v75
	s_waitcnt lgkmcnt(0)
	s_barrier
